# v26 + scan phase: partial-tile bf16 pack and LDS writes interleaved with the last two state-update MFMAs (published two MFMAs earlier)
# baseline (speedup 1.0000x reference)
.Lp2b_in_5:
	v_mfma_f32_32x32x16_bf16 v[2:17], v[118:121], v[150:153], v[2:17]
	v_mfma_f32_32x32x16_bf16 v[2:17], v[122:125], v[154:157], v[2:17]
	s_nop 7
	v_cvt_pk_bf16_f32 v18, v18, v19
	v_cvt_pk_bf16_f32 v19, v20, v21
	v_cvt_pk_bf16_f32 v20, v22, v23
	v_cvt_pk_bf16_f32 v21, v24, v25
	v_cvt_pk_bf16_f32 v22, v26, v27
	v_cvt_pk_bf16_f32 v23, v28, v29
	v_cvt_pk_bf16_f32 v24, v30, v31
	v_cvt_pk_bf16_f32 v25, v32, v33
	ds_write_b128 v192, v[18:21]
	ds_write_b128 v192, v[22:25] offset:1024
	v_mfma_f32_32x32x16_bf16 v[2:17], v[126:129], v[158:161], v[2:17]
	v_cvt_pk_bf16_f32 v34, v34, v35
	v_cvt_pk_bf16_f32 v35, v36, v37
	v_cvt_pk_bf16_f32 v36, v38, v39
	v_cvt_pk_bf16_f32 v37, v40, v41
	v_cvt_pk_bf16_f32 v38, v42, v43
	v_cvt_pk_bf16_f32 v39, v44, v45
	v_cvt_pk_bf16_f32 v40, v46, v47
	v_cvt_pk_bf16_f32 v41, v48, v49
	ds_write_b128 v192, v[34:37] offset:2048
	ds_write_b128 v192, v[38:41] offset:3072
	v_mfma_f32_32x32x16_bf16 v[2:17], v[130:133], v[162:165], v[2:17]
	s_waitcnt lgkmcnt(0)
	s_barrier
	ds_read2st64_b64 v[18:21], v193 offset0:0 offset1:8
	ds_read2st64_b64 v[22:25], v193 offset0:16 offset1:24
	ds_read2st64_b64 v[26:29], v193 offset0:32 offset1:40
	ds_read2st64_b64 v[30:33], v193 offset0:48 offset1:56
	ds_read_b128 v[150:153], v195 offset:4096
	ds_read_b128 v[154:157], v195 offset:5120
	ds_read_b128 v[158:161], v195 offset:6144
	ds_read_b128 v[162:165], v195 offset:7168
	ds_read_b128 v[166:169], v196 offset:4096
	s_waitcnt lgkmcnt(8)
	v_lshlrev_b32_e32 v178, 16, v18
	v_and_b32_e32 v179, 0xffff0000, v18
	v_lshlrev_b32_e32 v180, 16, v19
	v_and_b32_e32 v181, 0xffff0000, v19
	v_add_f32_e32 v174, 0, v178
	v_add_f32_e32 v175, 0, v179
	v_add_f32_e32 v176, 0, v180
	v_add_f32_e32 v177, 0, v181
	v_lshlrev_b32_e32 v178, 16, v20
	v_and_b32_e32 v179, 0xffff0000, v20
	v_lshlrev_b32_e32 v180, 16, v21
	v_and_b32_e32 v181, 0xffff0000, v21
	v_add_f32_e32 v174, v174, v178
	v_add_f32_e32 v175, v175, v179
	v_add_f32_e32 v176, v176, v180
	v_add_f32_e32 v177, v177, v181
	s_waitcnt lgkmcnt(7)
	v_lshlrev_b32_e32 v178, 16, v22
	v_and_b32_e32 v179, 0xffff0000, v22
	v_lshlrev_b32_e32 v180, 16, v23
	v_and_b32_e32 v181, 0xffff0000, v23
	v_add_f32_e32 v174, v174, v178
	v_add_f32_e32 v175, v175, v179
	v_add_f32_e32 v176, v176, v180
	v_add_f32_e32 v177, v177, v181
	v_lshlrev_b32_e32 v178, 16, v24
	v_and_b32_e32 v179, 0xffff0000, v24
	v_lshlrev_b32_e32 v180, 16, v25
	v_and_b32_e32 v181, 0xffff0000, v25
	v_add_f32_e32 v174, v174, v178
	v_add_f32_e32 v175, v175, v179
	v_add_f32_e32 v176, v176, v180
	v_add_f32_e32 v177, v177, v181
	s_waitcnt lgkmcnt(6)
	v_lshlrev_b32_e32 v178, 16, v26
	v_and_b32_e32 v179, 0xffff0000, v26
	v_lshlrev_b32_e32 v180, 16, v27
	v_and_b32_e32 v181, 0xffff0000, v27
	v_add_f32_e32 v174, v174, v178
	v_add_f32_e32 v175, v175, v179
	v_add_f32_e32 v176, v176, v180
	v_add_f32_e32 v177, v177, v181
	v_lshlrev_b32_e32 v178, 16, v28
	v_and_b32_e32 v179, 0xffff0000, v28
	v_lshlrev_b32_e32 v180, 16, v29
	v_and_b32_e32 v181, 0xffff0000, v29
	v_add_f32_e32 v174, v174, v178
	v_add_f32_e32 v175, v175, v179
	v_add_f32_e32 v176, v176, v180
	v_add_f32_e32 v177, v177, v181
	s_waitcnt lgkmcnt(5)
	v_lshlrev_b32_e32 v178, 16, v30
	v_and_b32_e32 v179, 0xffff0000, v30
	v_lshlrev_b32_e32 v180, 16, v31
	v_and_b32_e32 v181, 0xffff0000, v31
	v_add_f32_e32 v174, v174, v178
	v_add_f32_e32 v175, v175, v179
	v_add_f32_e32 v176, v176, v180
	v_add_f32_e32 v177, v177, v181
	v_lshlrev_b32_e32 v178, 16, v32
	v_and_b32_e32 v179, 0xffff0000, v32
	v_lshlrev_b32_e32 v180, 16, v33
	v_and_b32_e32 v181, 0xffff0000, v33
	v_add_f32_e32 v174, v174, v178
	v_add_f32_e32 v175, v175, v179
	v_add_f32_e32 v176, v176, v180
	v_add_f32_e32 v177, v177, v181
	v_mul_f32_e32 v174, v186, v174
	v_mul_f32_e32 v175, v187, v175
	v_mul_f32_e32 v176, v188, v176
	v_mul_f32_e32 v177, v189, v177
	v_bfe_u32 v178, v174, 16, 1
	v_bfe_u32 v179, v175, 16, 1
	v_bfe_u32 v180, v176, 16, 1
	v_bfe_u32 v181, v177, 16, 1
	v_add3_u32 v174, v174, v178, s23
	v_add3_u32 v175, v175, v179, s23
	v_add3_u32 v176, v176, v180, s23
	v_add3_u32 v177, v177, v181, s23
	global_store_short_d16_hi v197, v174, s[20:21] offset:-4096
	global_store_short_d16_hi v197, v175, s[20:21]
	global_store_short_d16_hi v198, v176, s[20:21] offset:-4096
	global_store_short_d16_hi v198, v177, s[20:21]
	s_add_u32 s20, s20, 0x40000
	s_addc_u32 s21, s21, 0
	s_waitcnt vmcnt(9)
	s_andn2_b64 vcc, exec, s[34:35]
	s_cbranch_vccnz .Lp2b_sv_6
	ds_write_b128 v194, v[170:173]
	global_load_dwordx4 v[170:173], v1, s[16:17]

.Lp2b_in_8:
	v_mfma_f32_32x32x16_bf16 v[2:17], v[134:137], v[150:153], v[2:17]
	v_mfma_f32_32x32x16_bf16 v[2:17], v[138:141], v[154:157], v[2:17]
	s_nop 7
	v_cvt_pk_bf16_f32 v18, v18, v19
	v_cvt_pk_bf16_f32 v19, v20, v21
	v_cvt_pk_bf16_f32 v20, v22, v23
	v_cvt_pk_bf16_f32 v21, v24, v25
	v_cvt_pk_bf16_f32 v22, v26, v27
	v_cvt_pk_bf16_f32 v23, v28, v29
	v_cvt_pk_bf16_f32 v24, v30, v31
	v_cvt_pk_bf16_f32 v25, v32, v33
	ds_write_b128 v192, v[18:21] offset:32768
	ds_write_b128 v192, v[22:25] offset:33792
	v_mfma_f32_32x32x16_bf16 v[2:17], v[142:145], v[158:161], v[2:17]
	v_cvt_pk_bf16_f32 v34, v34, v35
	v_cvt_pk_bf16_f32 v35, v36, v37
	v_cvt_pk_bf16_f32 v36, v38, v39
	v_cvt_pk_bf16_f32 v37, v40, v41
	v_cvt_pk_bf16_f32 v38, v42, v43
	v_cvt_pk_bf16_f32 v39, v44, v45
	v_cvt_pk_bf16_f32 v40, v46, v47
	v_cvt_pk_bf16_f32 v41, v48, v49
	ds_write_b128 v192, v[34:37] offset:34816
	ds_write_b128 v192, v[38:41] offset:35840
	v_mfma_f32_32x32x16_bf16 v[2:17], v[146:149], v[162:165], v[2:17]
	s_waitcnt lgkmcnt(0)
	s_barrier
	ds_read2st64_b64 v[18:21], v193 offset0:64 offset1:72
	ds_read2st64_b64 v[22:25], v193 offset0:80 offset1:88
	ds_read2st64_b64 v[26:29], v193 offset0:96 offset1:104
	ds_read2st64_b64 v[30:33], v193 offset0:112 offset1:120
	ds_read_b128 v[150:153], v195
	ds_read_b128 v[154:157], v195 offset:1024
	ds_read_b128 v[158:161], v195 offset:2048
	ds_read_b128 v[162:165], v195 offset:3072
	ds_read_b128 v[166:169], v196
	s_waitcnt lgkmcnt(8)
	v_lshlrev_b32_e32 v178, 16, v18
	v_and_b32_e32 v179, 0xffff0000, v18
	v_lshlrev_b32_e32 v180, 16, v19
	v_and_b32_e32 v181, 0xffff0000, v19
	v_add_f32_e32 v174, 0, v178
	v_add_f32_e32 v175, 0, v179
	v_add_f32_e32 v176, 0, v180
	v_add_f32_e32 v177, 0, v181
	v_lshlrev_b32_e32 v178, 16, v20
	v_and_b32_e32 v179, 0xffff0000, v20
	v_lshlrev_b32_e32 v180, 16, v21
	v_and_b32_e32 v181, 0xffff0000, v21
	v_add_f32_e32 v174, v174, v178
	v_add_f32_e32 v175, v175, v179
	v_add_f32_e32 v176, v176, v180
	v_add_f32_e32 v177, v177, v181
	s_waitcnt lgkmcnt(7)
	v_lshlrev_b32_e32 v178, 16, v22
	v_and_b32_e32 v179, 0xffff0000, v22
	v_lshlrev_b32_e32 v180, 16, v23
	v_and_b32_e32 v181, 0xffff0000, v23
	v_add_f32_e32 v174, v174, v178
	v_add_f32_e32 v175, v175, v179
	v_add_f32_e32 v176, v176, v180
	v_add_f32_e32 v177, v177, v181
	v_lshlrev_b32_e32 v178, 16, v24
	v_and_b32_e32 v179, 0xffff0000, v24
	v_lshlrev_b32_e32 v180, 16, v25
	v_and_b32_e32 v181, 0xffff0000, v25
	v_add_f32_e32 v174, v174, v178
	v_add_f32_e32 v175, v175, v179
	v_add_f32_e32 v176, v176, v180
	v_add_f32_e32 v177, v177, v181
	s_waitcnt lgkmcnt(6)
	v_lshlrev_b32_e32 v178, 16, v26
	v_and_b32_e32 v179, 0xffff0000, v26
	v_lshlrev_b32_e32 v180, 16, v27
	v_and_b32_e32 v181, 0xffff0000, v27
	v_add_f32_e32 v174, v174, v178
	v_add_f32_e32 v175, v175, v179
	v_add_f32_e32 v176, v176, v180
	v_add_f32_e32 v177, v177, v181
	v_lshlrev_b32_e32 v178, 16, v28
	v_and_b32_e32 v179, 0xffff0000, v28
	v_lshlrev_b32_e32 v180, 16, v29
	v_and_b32_e32 v181, 0xffff0000, v29
	v_add_f32_e32 v174, v174, v178
	v_add_f32_e32 v175, v175, v179
	v_add_f32_e32 v176, v176, v180
	v_add_f32_e32 v177, v177, v181
	s_waitcnt lgkmcnt(5)
	v_lshlrev_b32_e32 v178, 16, v30
	v_and_b32_e32 v179, 0xffff0000, v30
	v_lshlrev_b32_e32 v180, 16, v31
	v_and_b32_e32 v181, 0xffff0000, v31
	v_add_f32_e32 v174, v174, v178
	v_add_f32_e32 v175, v175, v179
	v_add_f32_e32 v176, v176, v180
	v_add_f32_e32 v177, v177, v181
	v_lshlrev_b32_e32 v178, 16, v32
	v_and_b32_e32 v179, 0xffff0000, v32
	v_lshlrev_b32_e32 v180, 16, v33
	v_and_b32_e32 v181, 0xffff0000, v33
	v_add_f32_e32 v174, v174, v178
	v_add_f32_e32 v175, v175, v179
	v_add_f32_e32 v176, v176, v180
	v_add_f32_e32 v177, v177, v181
	v_mul_f32_e32 v174, v186, v174
	v_mul_f32_e32 v175, v187, v175
	v_mul_f32_e32 v176, v188, v176
	v_mul_f32_e32 v177, v189, v177
	v_bfe_u32 v178, v174, 16, 1
	v_bfe_u32 v179, v175, 16, 1
	v_bfe_u32 v180, v176, 16, 1
	v_bfe_u32 v181, v177, 16, 1
	v_add3_u32 v174, v174, v178, s23
	v_add3_u32 v175, v175, v179, s23
	v_add3_u32 v176, v176, v180, s23
	v_add3_u32 v177, v177, v181, s23
	global_store_short_d16_hi v197, v174, s[20:21] offset:-4096
	global_store_short_d16_hi v197, v175, s[20:21]
	global_store_short_d16_hi v198, v176, s[20:21] offset:-4096
	global_store_short_d16_hi v198, v177, s[20:21]
	s_add_u32 s20, s20, 0x40000
	s_addc_u32 s21, s21, 0
	s_waitcnt vmcnt(9)
	s_andn2_b64 vcc, exec, s[34:35]
	s_cbranch_vccnz .Lp2b_sv_9
	ds_write_b128 v194, v[170:173] offset:4096
	global_load_dwordx4 v[170:173], v1, s[16:17]

; __device__ __forceinline__ void scan_phase(const bf16* q, const bf16* kdT, const bf16* vT, const bf16* Pp, bf16* o, LAS unsigned char* lds, int bid, int G, int wave, int lane, int tid) {
;     ...
;         for (int i = 0; i < 60; i += 6) { SCAN_STEP(0, 2, 0, 1, i); SCAN_STEP(1, 0, 1, 0, i + 1); SCAN_STEP(2, 1, 0, 1, i + 2); SCAN_STEP(0, 2, 1, 0, i + 3); SCAN_STEP(1, 0, 0, 1, i + 4); SCAN_STEP(2, 1, 1, 0, i + 5); }
.Lp2b_in_20:
	v_mfma_f32_32x32x16_bf16 v[2:17], v[134:137], v[150:153], v[2:17]
	v_mfma_f32_32x32x16_bf16 v[2:17], v[138:141], v[154:157], v[2:17]
	s_nop 7
	v_cvt_pk_bf16_f32 v18, v18, v19
	v_cvt_pk_bf16_f32 v19, v20, v21
	v_cvt_pk_bf16_f32 v20, v22, v23
	v_cvt_pk_bf16_f32 v21, v24, v25
	v_cvt_pk_bf16_f32 v22, v26, v27
	v_cvt_pk_bf16_f32 v23, v28, v29
	v_cvt_pk_bf16_f32 v24, v30, v31
	v_cvt_pk_bf16_f32 v25, v32, v33
	ds_write_b128 v192, v[18:21] offset:32768
	ds_write_b128 v192, v[22:25] offset:33792
	v_mfma_f32_32x32x16_bf16 v[2:17], v[142:145], v[158:161], v[2:17]
	v_cvt_pk_bf16_f32 v34, v34, v35
	v_cvt_pk_bf16_f32 v35, v36, v37
	v_cvt_pk_bf16_f32 v36, v38, v39
	v_cvt_pk_bf16_f32 v37, v40, v41
	v_cvt_pk_bf16_f32 v38, v42, v43
	v_cvt_pk_bf16_f32 v39, v44, v45
	v_cvt_pk_bf16_f32 v40, v46, v47
	v_cvt_pk_bf16_f32 v41, v48, v49
	ds_write_b128 v192, v[34:37] offset:34816
	ds_write_b128 v192, v[38:41] offset:35840
	v_mfma_f32_32x32x16_bf16 v[2:17], v[146:149], v[162:165], v[2:17]
	s_waitcnt lgkmcnt(0)
	s_barrier
	ds_read2st64_b64 v[18:21], v193 offset0:64 offset1:72
	ds_read2st64_b64 v[22:25], v193 offset0:80 offset1:88
	ds_read2st64_b64 v[26:29], v193 offset0:96 offset1:104
	ds_read2st64_b64 v[30:33], v193 offset0:112 offset1:120
	ds_read_b128 v[150:153], v195
	ds_read_b128 v[154:157], v195 offset:1024
	ds_read_b128 v[158:161], v195 offset:2048
	ds_read_b128 v[162:165], v195 offset:3072
	ds_read_b128 v[166:169], v196
	s_waitcnt lgkmcnt(8)
	v_lshlrev_b32_e32 v178, 16, v18
	v_and_b32_e32 v179, 0xffff0000, v18
	v_lshlrev_b32_e32 v180, 16, v19
	v_and_b32_e32 v181, 0xffff0000, v19
	v_add_f32_e32 v174, 0, v178
	v_add_f32_e32 v175, 0, v179
	v_add_f32_e32 v176, 0, v180
	v_add_f32_e32 v177, 0, v181
	v_lshlrev_b32_e32 v178, 16, v20
	v_and_b32_e32 v179, 0xffff0000, v20
	v_lshlrev_b32_e32 v180, 16, v21
	v_and_b32_e32 v181, 0xffff0000, v21
	v_add_f32_e32 v174, v174, v178
	v_add_f32_e32 v175, v175, v179
	v_add_f32_e32 v176, v176, v180
	v_add_f32_e32 v177, v177, v181
	s_waitcnt lgkmcnt(7)
	v_lshlrev_b32_e32 v178, 16, v22
	v_and_b32_e32 v179, 0xffff0000, v22
	v_lshlrev_b32_e32 v180, 16, v23
	v_and_b32_e32 v181, 0xffff0000, v23
	v_add_f32_e32 v174, v174, v178
	v_add_f32_e32 v175, v175, v179
	v_add_f32_e32 v176, v176, v180
	v_add_f32_e32 v177, v177, v181
	v_lshlrev_b32_e32 v178, 16, v24
	v_and_b32_e32 v179, 0xffff0000, v24
	v_lshlrev_b32_e32 v180, 16, v25
	v_and_b32_e32 v181, 0xffff0000, v25
	v_add_f32_e32 v174, v174, v178
	v_add_f32_e32 v175, v175, v179
	v_add_f32_e32 v176, v176, v180
	v_add_f32_e32 v177, v177, v181
	s_waitcnt lgkmcnt(6)
	v_lshlrev_b32_e32 v178, 16, v26
	v_and_b32_e32 v179, 0xffff0000, v26
	v_lshlrev_b32_e32 v180, 16, v27
	v_and_b32_e32 v181, 0xffff0000, v27
	v_add_f32_e32 v174, v174, v178
	v_add_f32_e32 v175, v175, v179
	v_add_f32_e32 v176, v176, v180
	v_add_f32_e32 v177, v177, v181
	v_lshlrev_b32_e32 v178, 16, v28
	v_and_b32_e32 v179, 0xffff0000, v28
	v_lshlrev_b32_e32 v180, 16, v29
	v_and_b32_e32 v181, 0xffff0000, v29
	v_add_f32_e32 v174, v174, v178
	v_add_f32_e32 v175, v175, v179
	v_add_f32_e32 v176, v176, v180
	v_add_f32_e32 v177, v177, v181
	s_waitcnt lgkmcnt(5)
	v_lshlrev_b32_e32 v178, 16, v30
	v_and_b32_e32 v179, 0xffff0000, v30
	v_lshlrev_b32_e32 v180, 16, v31
	v_and_b32_e32 v181, 0xffff0000, v31
	v_add_f32_e32 v174, v174, v178
	v_add_f32_e32 v175, v175, v179
	v_add_f32_e32 v176, v176, v180
	v_add_f32_e32 v177, v177, v181
	v_lshlrev_b32_e32 v178, 16, v32
	v_and_b32_e32 v179, 0xffff0000, v32
	v_lshlrev_b32_e32 v180, 16, v33
	v_and_b32_e32 v181, 0xffff0000, v33
	v_add_f32_e32 v174, v174, v178
	v_add_f32_e32 v175, v175, v179
	v_add_f32_e32 v176, v176, v180
	v_add_f32_e32 v177, v177, v181
	v_mul_f32_e32 v174, v186, v174
	v_mul_f32_e32 v175, v187, v175
	v_mul_f32_e32 v176, v188, v176
	v_mul_f32_e32 v177, v189, v177
	v_bfe_u32 v178, v174, 16, 1
	v_bfe_u32 v179, v175, 16, 1
	v_bfe_u32 v180, v176, 16, 1
	v_bfe_u32 v181, v177, 16, 1
	v_add3_u32 v174, v174, v178, s23
	v_add3_u32 v175, v175, v179, s23
	v_add3_u32 v176, v176, v180, s23
	v_add3_u32 v177, v177, v181, s23
	global_store_short_d16_hi v197, v174, s[20:21] offset:-4096
	global_store_short_d16_hi v197, v175, s[20:21]
	global_store_short_d16_hi v198, v176, s[20:21] offset:-4096
	global_store_short_d16_hi v198, v177, s[20:21]
	s_add_u32 s20, s20, 0x40000
	s_addc_u32 s21, s21, 0
	s_add_i32 s22, s22, 1
	s_cmp_lt_u32 s22, 10
	s_cbranch_scc1 .Lp2b_loop
	s_waitcnt vmcnt(9)
	s_andn2_b64 vcc, exec, s[34:35]
	s_cbranch_vccnz .Lp2b_sv_21
	ds_write_b128 v194, v[170:173] offset:4096
	global_load_dwordx4 v[170:173], v1, s[16:17]

; __device__ __forceinline__ void scan_phase(const bf16* q, const bf16* kdT, const bf16* vT, const bf16* Pp, bf16* o, LAS unsigned char* lds, int bid, int G, int wave, int lane, int tid) {
;     ...
;         SCAN_STEP(0, 2, 0, 1, 60); SCAN_STEP(1, 0, 1, 0, 61); SCAN_STEP(2, 1, 0, 1, 62); SCAN_STEP(0, 2, 1, 0, 63);
.Lp2b_in_26:
	v_mfma_f32_32x32x16_bf16 v[2:17], v[134:137], v[150:153], v[2:17]
	v_mfma_f32_32x32x16_bf16 v[2:17], v[138:141], v[154:157], v[2:17]
	s_nop 7
	v_cvt_pk_bf16_f32 v18, v18, v19
	v_cvt_pk_bf16_f32 v19, v20, v21
	v_cvt_pk_bf16_f32 v20, v22, v23
	v_cvt_pk_bf16_f32 v21, v24, v25
	v_cvt_pk_bf16_f32 v22, v26, v27
	v_cvt_pk_bf16_f32 v23, v28, v29
	v_cvt_pk_bf16_f32 v24, v30, v31
	v_cvt_pk_bf16_f32 v25, v32, v33
	ds_write_b128 v192, v[18:21] offset:32768
	ds_write_b128 v192, v[22:25] offset:33792
	v_mfma_f32_32x32x16_bf16 v[2:17], v[142:145], v[158:161], v[2:17]
	v_cvt_pk_bf16_f32 v34, v34, v35
	v_cvt_pk_bf16_f32 v35, v36, v37
	v_cvt_pk_bf16_f32 v36, v38, v39
	v_cvt_pk_bf16_f32 v37, v40, v41
	v_cvt_pk_bf16_f32 v38, v42, v43
	v_cvt_pk_bf16_f32 v39, v44, v45
	v_cvt_pk_bf16_f32 v40, v46, v47
	v_cvt_pk_bf16_f32 v41, v48, v49
	ds_write_b128 v192, v[34:37] offset:34816
	ds_write_b128 v192, v[38:41] offset:35840
	v_mfma_f32_32x32x16_bf16 v[2:17], v[146:149], v[162:165], v[2:17]
	s_waitcnt lgkmcnt(0)
	s_barrier
	ds_read2st64_b64 v[18:21], v193 offset0:64 offset1:72
	ds_read2st64_b64 v[22:25], v193 offset0:80 offset1:88
	ds_read2st64_b64 v[26:29], v193 offset0:96 offset1:104
	ds_read2st64_b64 v[30:33], v193 offset0:112 offset1:120
	ds_read_b128 v[150:153], v195
	ds_read_b128 v[154:157], v195 offset:1024
	ds_read_b128 v[158:161], v195 offset:2048
	ds_read_b128 v[162:165], v195 offset:3072
	ds_read_b128 v[166:169], v196
	s_waitcnt lgkmcnt(8)
	v_lshlrev_b32_e32 v178, 16, v18
	v_and_b32_e32 v179, 0xffff0000, v18
	v_lshlrev_b32_e32 v180, 16, v19
	v_and_b32_e32 v181, 0xffff0000, v19
	v_add_f32_e32 v174, 0, v178
	v_add_f32_e32 v175, 0, v179
	v_add_f32_e32 v176, 0, v180
	v_add_f32_e32 v177, 0, v181
	v_lshlrev_b32_e32 v178, 16, v20
	v_and_b32_e32 v179, 0xffff0000, v20
	v_lshlrev_b32_e32 v180, 16, v21
	v_and_b32_e32 v181, 0xffff0000, v21
	v_add_f32_e32 v174, v174, v178
	v_add_f32_e32 v175, v175, v179
	v_add_f32_e32 v176, v176, v180
	v_add_f32_e32 v177, v177, v181
	s_waitcnt lgkmcnt(7)
	v_lshlrev_b32_e32 v178, 16, v22
	v_and_b32_e32 v179, 0xffff0000, v22
	v_lshlrev_b32_e32 v180, 16, v23
	v_and_b32_e32 v181, 0xffff0000, v23
	v_add_f32_e32 v174, v174, v178
	v_add_f32_e32 v175, v175, v179
	v_add_f32_e32 v176, v176, v180
	v_add_f32_e32 v177, v177, v181
	v_lshlrev_b32_e32 v178, 16, v24
	v_and_b32_e32 v179, 0xffff0000, v24
	v_lshlrev_b32_e32 v180, 16, v25
	v_and_b32_e32 v181, 0xffff0000, v25
	v_add_f32_e32 v174, v174, v178
	v_add_f32_e32 v175, v175, v179
	v_add_f32_e32 v176, v176, v180
	v_add_f32_e32 v177, v177, v181
	s_waitcnt lgkmcnt(6)
	v_lshlrev_b32_e32 v178, 16, v26
	v_and_b32_e32 v179, 0xffff0000, v26
	v_lshlrev_b32_e32 v180, 16, v27
	v_and_b32_e32 v181, 0xffff0000, v27
	v_add_f32_e32 v174, v174, v178
	v_add_f32_e32 v175, v175, v179
	v_add_f32_e32 v176, v176, v180
	v_add_f32_e32 v177, v177, v181
	v_lshlrev_b32_e32 v178, 16, v28
	v_and_b32_e32 v179, 0xffff0000, v28
	v_lshlrev_b32_e32 v180, 16, v29
	v_and_b32_e32 v181, 0xffff0000, v29
	v_add_f32_e32 v174, v174, v178
	v_add_f32_e32 v175, v175, v179
	v_add_f32_e32 v176, v176, v180
	v_add_f32_e32 v177, v177, v181
	s_waitcnt lgkmcnt(5)
	v_lshlrev_b32_e32 v178, 16, v30
	v_and_b32_e32 v179, 0xffff0000, v30
	v_lshlrev_b32_e32 v180, 16, v31
	v_and_b32_e32 v181, 0xffff0000, v31
	v_add_f32_e32 v174, v174, v178
	v_add_f32_e32 v175, v175, v179
	v_add_f32_e32 v176, v176, v180
	v_add_f32_e32 v177, v177, v181
	v_lshlrev_b32_e32 v178, 16, v32
	v_and_b32_e32 v179, 0xffff0000, v32
	v_lshlrev_b32_e32 v180, 16, v33
	v_and_b32_e32 v181, 0xffff0000, v33
	v_add_f32_e32 v174, v174, v178
	v_add_f32_e32 v175, v175, v179
	v_add_f32_e32 v176, v176, v180
	v_add_f32_e32 v177, v177, v181
	v_mul_f32_e32 v174, v186, v174
	v_mul_f32_e32 v175, v187, v175
	v_mul_f32_e32 v176, v188, v176
	v_mul_f32_e32 v177, v189, v177
	v_bfe_u32 v178, v174, 16, 1
	v_bfe_u32 v179, v175, 16, 1
	v_bfe_u32 v180, v176, 16, 1
	v_bfe_u32 v181, v177, 16, 1
	v_add3_u32 v174, v174, v178, s23
	v_add3_u32 v175, v175, v179, s23
	v_add3_u32 v176, v176, v180, s23
	v_add3_u32 v177, v177, v181, s23
	global_store_short_d16_hi v197, v174, s[20:21] offset:-4096
	global_store_short_d16_hi v197, v175, s[20:21]
	global_store_short_d16_hi v198, v176, s[20:21] offset:-4096
	global_store_short_d16_hi v198, v177, s[20:21]
	s_add_u32 s20, s20, 0x40000
	s_addc_u32 s21, s21, 0
	s_waitcnt vmcnt(9)
	s_andn2_b64 vcc, exec, s[34:35]
	s_cbranch_vccnz .Lp2b_sv_27
	ds_write_b128 v194, v[170:173] offset:4096

.Lp2b_in_29:
	v_mfma_f32_32x32x16_bf16 v[2:17], v[118:121], v[150:153], v[2:17]
	v_mfma_f32_32x32x16_bf16 v[2:17], v[122:125], v[154:157], v[2:17]
	s_nop 7
	v_cvt_pk_bf16_f32 v18, v18, v19
	v_cvt_pk_bf16_f32 v19, v20, v21
	v_cvt_pk_bf16_f32 v20, v22, v23
	v_cvt_pk_bf16_f32 v21, v24, v25
	v_cvt_pk_bf16_f32 v22, v26, v27
	v_cvt_pk_bf16_f32 v23, v28, v29
	v_cvt_pk_bf16_f32 v24, v30, v31
	v_cvt_pk_bf16_f32 v25, v32, v33
	ds_write_b128 v192, v[18:21]
	ds_write_b128 v192, v[22:25] offset:1024
	v_mfma_f32_32x32x16_bf16 v[2:17], v[126:129], v[158:161], v[2:17]
	v_cvt_pk_bf16_f32 v34, v34, v35
	v_cvt_pk_bf16_f32 v35, v36, v37
	v_cvt_pk_bf16_f32 v36, v38, v39
	v_cvt_pk_bf16_f32 v37, v40, v41
	v_cvt_pk_bf16_f32 v38, v42, v43
	v_cvt_pk_bf16_f32 v39, v44, v45
	v_cvt_pk_bf16_f32 v40, v46, v47
	v_cvt_pk_bf16_f32 v41, v48, v49
	ds_write_b128 v192, v[34:37] offset:2048
	ds_write_b128 v192, v[38:41] offset:3072
	v_mfma_f32_32x32x16_bf16 v[2:17], v[130:133], v[162:165], v[2:17]
	s_waitcnt lgkmcnt(0)
	s_barrier
	ds_read2st64_b64 v[18:21], v193 offset0:0 offset1:8
	ds_read2st64_b64 v[22:25], v193 offset0:16 offset1:24
	ds_read2st64_b64 v[26:29], v193 offset0:32 offset1:40
	ds_read2st64_b64 v[30:33], v193 offset0:48 offset1:56
	ds_read_b128 v[150:153], v195 offset:4096
	ds_read_b128 v[154:157], v195 offset:5120
	ds_read_b128 v[158:161], v195 offset:6144
	ds_read_b128 v[162:165], v195 offset:7168
	ds_read_b128 v[166:169], v196 offset:4096
	s_waitcnt lgkmcnt(8)
	v_lshlrev_b32_e32 v178, 16, v18
	v_and_b32_e32 v179, 0xffff0000, v18
	v_lshlrev_b32_e32 v180, 16, v19
	v_and_b32_e32 v181, 0xffff0000, v19
	v_add_f32_e32 v174, 0, v178
	v_add_f32_e32 v175, 0, v179
	v_add_f32_e32 v176, 0, v180
	v_add_f32_e32 v177, 0, v181
	v_lshlrev_b32_e32 v178, 16, v20
	v_and_b32_e32 v179, 0xffff0000, v20
	v_lshlrev_b32_e32 v180, 16, v21
	v_and_b32_e32 v181, 0xffff0000, v21
	v_add_f32_e32 v174, v174, v178
	v_add_f32_e32 v175, v175, v179
	v_add_f32_e32 v176, v176, v180
	v_add_f32_e32 v177, v177, v181
	s_waitcnt lgkmcnt(7)
	v_lshlrev_b32_e32 v178, 16, v22
	v_and_b32_e32 v179, 0xffff0000, v22
	v_lshlrev_b32_e32 v180, 16, v23
	v_and_b32_e32 v181, 0xffff0000, v23
	v_add_f32_e32 v174, v174, v178
	v_add_f32_e32 v175, v175, v179
	v_add_f32_e32 v176, v176, v180
	v_add_f32_e32 v177, v177, v181
	v_lshlrev_b32_e32 v178, 16, v24
	v_and_b32_e32 v179, 0xffff0000, v24
	v_lshlrev_b32_e32 v180, 16, v25
	v_and_b32_e32 v181, 0xffff0000, v25
	v_add_f32_e32 v174, v174, v178
	v_add_f32_e32 v175, v175, v179
	v_add_f32_e32 v176, v176, v180
	v_add_f32_e32 v177, v177, v181
	s_waitcnt lgkmcnt(6)
	v_lshlrev_b32_e32 v178, 16, v26
	v_and_b32_e32 v179, 0xffff0000, v26
	v_lshlrev_b32_e32 v180, 16, v27
	v_and_b32_e32 v181, 0xffff0000, v27
	v_add_f32_e32 v174, v174, v178
	v_add_f32_e32 v175, v175, v179
	v_add_f32_e32 v176, v176, v180
	v_add_f32_e32 v177, v177, v181
	v_lshlrev_b32_e32 v178, 16, v28
	v_and_b32_e32 v179, 0xffff0000, v28
	v_lshlrev_b32_e32 v180, 16, v29
	v_and_b32_e32 v181, 0xffff0000, v29
	v_add_f32_e32 v174, v174, v178
	v_add_f32_e32 v175, v175, v179
	v_add_f32_e32 v176, v176, v180
	v_add_f32_e32 v177, v177, v181
	s_waitcnt lgkmcnt(5)
	v_lshlrev_b32_e32 v178, 16, v30
	v_and_b32_e32 v179, 0xffff0000, v30
	v_lshlrev_b32_e32 v180, 16, v31
	v_and_b32_e32 v181, 0xffff0000, v31
	v_add_f32_e32 v174, v174, v178
	v_add_f32_e32 v175, v175, v179
	v_add_f32_e32 v176, v176, v180
	v_add_f32_e32 v177, v177, v181
	v_lshlrev_b32_e32 v178, 16, v32
	v_and_b32_e32 v179, 0xffff0000, v32
	v_lshlrev_b32_e32 v180, 16, v33
	v_and_b32_e32 v181, 0xffff0000, v33
	v_add_f32_e32 v174, v174, v178
	v_add_f32_e32 v175, v175, v179
	v_add_f32_e32 v176, v176, v180
	v_add_f32_e32 v177, v177, v181
	v_mul_f32_e32 v174, v186, v174
	v_mul_f32_e32 v175, v187, v175
	v_mul_f32_e32 v176, v188, v176
	v_mul_f32_e32 v177, v189, v177
	v_bfe_u32 v178, v174, 16, 1
	v_bfe_u32 v179, v175, 16, 1
	v_bfe_u32 v180, v176, 16, 1
	v_bfe_u32 v181, v177, 16, 1
	v_add3_u32 v174, v174, v178, s23
	v_add3_u32 v175, v175, v179, s23
	v_add3_u32 v176, v176, v180, s23
	v_add3_u32 v177, v177, v181, s23
	global_store_short_d16_hi v197, v174, s[20:21] offset:-4096
	global_store_short_d16_hi v197, v175, s[20:21]
	global_store_short_d16_hi v198, v176, s[20:21] offset:-4096
	global_store_short_d16_hi v198, v177, s[20:21]
	s_add_u32 s20, s20, 0x40000
	s_addc_u32 s21, s21, 0
	s_waitcnt vmcnt(4)
	v_cvt_pk_bf16_f32 v50, v2, v3
	v_cvt_pk_bf16_f32 v51, v4, v5
	v_cvt_pk_bf16_f32 v52, v6, v7
	v_cvt_pk_bf16_f32 v53, v8, v9
	v_cvt_pk_bf16_f32 v54, v10, v11
	v_cvt_pk_bf16_f32 v55, v12, v13
	v_cvt_pk_bf16_f32 v56, v14, v15
	v_cvt_pk_bf16_f32 v57, v16, v17
	v_mfma_f32_32x32x16_bf16 v[18:33], v[58:61], v[50:53], 0
	v_mfma_f32_32x32x16_bf16 v[34:49], v[66:69], v[50:53], 0
	v_mfma_f32_32x32x16_bf16 v[18:33], v[62:65], v[54:57], v[18:33]
	v_mfma_f32_32x32x16_bf16 v[34:49], v[70:73], v[54:57], v[34:49]
	v_mul_f32_e32 v2, v190, v2
	v_mul_f32_e32 v3, v190, v3
	v_mul_f32_e32 v4, v190, v4
	v_mul_f32_e32 v5, v190, v5
	v_mul_f32_e32 v6, v190, v6
	v_mul_f32_e32 v7, v190, v7
	v_mul_f32_e32 v8, v190, v8
	v_mul_f32_e32 v9, v190, v9
	v_mul_f32_e32 v10, v190, v10
	v_mul_f32_e32 v11, v190, v11
	v_mul_f32_e32 v12, v190, v12
	v_mul_f32_e32 v13, v190, v13
	v_mul_f32_e32 v14, v190, v14
	v_mul_f32_e32 v15, v190, v15
	v_mul_f32_e32 v16, v190, v16
	v_mul_f32_e32 v17, v190, v17
	s_waitcnt lgkmcnt(0)
	s_cmp_eq_u32 s7, 0
	s_cbranch_scc0 .Lp2b_in_30
	v_mfma_f32_32x32x16_bf16 v[18:33], v[74:77], v[166:169], v[18:33]
	s_branch .Lp2b_in_31

; __device__ __forceinline__ void scan_phase(const bf16* q, const bf16* kdT, const bf16* vT, const bf16* Pp, bf16* o, LAS unsigned char* lds, int bid, int G, int wave, int lane, int tid) {
;     ...
;         __syncthreads();
.Lp2b_in_31:
	v_mfma_f32_32x32x16_bf16 v[2:17], v[134:137], v[150:153], v[2:17]
	v_mfma_f32_32x32x16_bf16 v[2:17], v[138:141], v[154:157], v[2:17]
	s_nop 7
	v_cvt_pk_bf16_f32 v18, v18, v19
	v_cvt_pk_bf16_f32 v19, v20, v21
	v_cvt_pk_bf16_f32 v20, v22, v23
	v_cvt_pk_bf16_f32 v21, v24, v25
	v_cvt_pk_bf16_f32 v22, v26, v27
	v_cvt_pk_bf16_f32 v23, v28, v29
	v_cvt_pk_bf16_f32 v24, v30, v31
	v_cvt_pk_bf16_f32 v25, v32, v33
	ds_write_b128 v192, v[18:21] offset:32768
	ds_write_b128 v192, v[22:25] offset:33792
	v_mfma_f32_32x32x16_bf16 v[2:17], v[142:145], v[158:161], v[2:17]
	v_cvt_pk_bf16_f32 v34, v34, v35
	v_cvt_pk_bf16_f32 v35, v36, v37
	v_cvt_pk_bf16_f32 v36, v38, v39
	v_cvt_pk_bf16_f32 v37, v40, v41
	v_cvt_pk_bf16_f32 v38, v42, v43
	v_cvt_pk_bf16_f32 v39, v44, v45
	v_cvt_pk_bf16_f32 v40, v46, v47
	v_cvt_pk_bf16_f32 v41, v48, v49
	ds_write_b128 v192, v[34:37] offset:34816
	ds_write_b128 v192, v[38:41] offset:35840
	v_mfma_f32_32x32x16_bf16 v[2:17], v[146:149], v[162:165], v[2:17]
	s_waitcnt lgkmcnt(0)
	s_barrier
	ds_read2st64_b64 v[18:21], v193 offset0:64 offset1:72
	ds_read2st64_b64 v[22:25], v193 offset0:80 offset1:88
	ds_read2st64_b64 v[26:29], v193 offset0:96 offset1:104
	ds_read2st64_b64 v[30:33], v193 offset0:112 offset1:120
	s_waitcnt lgkmcnt(3)
	v_lshlrev_b32_e32 v178, 16, v18
	v_and_b32_e32 v179, 0xffff0000, v18
	v_lshlrev_b32_e32 v180, 16, v19
	v_and_b32_e32 v181, 0xffff0000, v19
	v_add_f32_e32 v174, 0, v178
	v_add_f32_e32 v175, 0, v179
	v_add_f32_e32 v176, 0, v180
	v_add_f32_e32 v177, 0, v181
	v_lshlrev_b32_e32 v178, 16, v20
	v_and_b32_e32 v179, 0xffff0000, v20
	v_lshlrev_b32_e32 v180, 16, v21
	v_and_b32_e32 v181, 0xffff0000, v21
	v_add_f32_e32 v174, v174, v178
	v_add_f32_e32 v175, v175, v179
	v_add_f32_e32 v176, v176, v180
	v_add_f32_e32 v177, v177, v181
	s_waitcnt lgkmcnt(2)
	v_lshlrev_b32_e32 v178, 16, v22
	v_and_b32_e32 v179, 0xffff0000, v22
	v_lshlrev_b32_e32 v180, 16, v23
	v_and_b32_e32 v181, 0xffff0000, v23
	v_add_f32_e32 v174, v174, v178
	v_add_f32_e32 v175, v175, v179
	v_add_f32_e32 v176, v176, v180
	v_add_f32_e32 v177, v177, v181
	v_lshlrev_b32_e32 v178, 16, v24
	v_and_b32_e32 v179, 0xffff0000, v24
	v_lshlrev_b32_e32 v180, 16, v25
	v_and_b32_e32 v181, 0xffff0000, v25
	v_add_f32_e32 v174, v174, v178
	v_add_f32_e32 v175, v175, v179
	v_add_f32_e32 v176, v176, v180
	v_add_f32_e32 v177, v177, v181
	s_waitcnt lgkmcnt(1)
	v_lshlrev_b32_e32 v178, 16, v26
	v_and_b32_e32 v179, 0xffff0000, v26
	v_lshlrev_b32_e32 v180, 16, v27
	v_and_b32_e32 v181, 0xffff0000, v27
	v_add_f32_e32 v174, v174, v178
	v_add_f32_e32 v175, v175, v179
	v_add_f32_e32 v176, v176, v180
	v_add_f32_e32 v177, v177, v181
	v_lshlrev_b32_e32 v178, 16, v28
	v_and_b32_e32 v179, 0xffff0000, v28
	v_lshlrev_b32_e32 v180, 16, v29
	v_and_b32_e32 v181, 0xffff0000, v29
	v_add_f32_e32 v174, v174, v178
	v_add_f32_e32 v175, v175, v179
	v_add_f32_e32 v176, v176, v180
	v_add_f32_e32 v177, v177, v181
	s_waitcnt lgkmcnt(0)
	v_lshlrev_b32_e32 v178, 16, v30
	v_and_b32_e32 v179, 0xffff0000, v30
	v_lshlrev_b32_e32 v180, 16, v31
	v_and_b32_e32 v181, 0xffff0000, v31
	v_add_f32_e32 v174, v174, v178
	v_add_f32_e32 v175, v175, v179
	v_add_f32_e32 v176, v176, v180
	v_add_f32_e32 v177, v177, v181
	v_lshlrev_b32_e32 v178, 16, v32
	v_and_b32_e32 v179, 0xffff0000, v32
	v_lshlrev_b32_e32 v180, 16, v33
	v_and_b32_e32 v181, 0xffff0000, v33
	v_add_f32_e32 v174, v174, v178
	v_add_f32_e32 v175, v175, v179
	v_add_f32_e32 v176, v176, v180
	v_add_f32_e32 v177, v177, v181
	v_mul_f32_e32 v174, v186, v174
	v_mul_f32_e32 v175, v187, v175
	v_mul_f32_e32 v176, v188, v176
	v_mul_f32_e32 v177, v189, v177
	v_bfe_u32 v178, v174, 16, 1
	v_bfe_u32 v179, v175, 16, 1
	v_bfe_u32 v180, v176, 16, 1
	v_bfe_u32 v181, v177, 16, 1
	v_add3_u32 v174, v174, v178, s23
	v_add3_u32 v175, v175, v179, s23
	v_add3_u32 v176, v176, v180, s23
	v_add3_u32 v177, v177, v181, s23
	global_store_short_d16_hi v197, v174, s[20:21] offset:-4096
	global_store_short_d16_hi v197, v175, s[20:21]
	global_store_short_d16_hi v198, v176, s[20:21] offset:-4096
	global_store_short_d16_hi v198, v177, s[20:21]
	s_add_u32 s20, s20, 0x40000
	s_addc_u32 s21, s21, 0
	s_barrier
	s_branch .LBB0_718
